# G1->mix (ph2->3, ph17->18) team syncs with neighbour-team waits (U halo rows), staged epilogue stores write-through
# speedup vs baseline: 1.0190x; 1.0040x over previous
G1E_ph2_ST:
	v_and_b32_e32 v223, 31, v0
	v_mul_u32_u24_e32 v220, 0x110, v223
	v_bfe_u32 v223, v0, 5, 1
	v_lshl_add_u32 v220, v223, 4, v220
	v_bfe_u32 v224, v0, 6, 2
	v_mul_u32_u24_e32 v223, 0x2200, v224
	v_add_u32_e32 v220, v220, v223
	v_bfe_u32 v222, v0, 4, 2
	v_mul_u32_u24_e32 v221, 0x110, v222
	v_add_u32_e32 v221, v221, v223
	v_and_b32_e32 v223, 15, v0
	v_lshl_add_u32 v221, v223, 4, v221
	s_and_b32 s84, s35, 63
	s_mulk_i32 s84, 0xc0
	s_lshr_b32 s85, s35, 6
	s_and_b32 s85, s85, 7
	s_lshl_b32 s85, s85, 8
	v_lshrrev_b32_e32 v224, 1, v224
	v_mul_u32_u24_e32 v224, 0x60, v224
	v_add3_u32 v222, v222, v224, s84
	v_lshlrev_b32_e32 v222, 11, v222
	v_lshl_add_u32 v222, v223, 3, v222
	v_bfe_u32 v223, v0, 6, 1
	v_lshl_add_u32 v222, v223, 7, v222
	v_add_u32_e32 v222, s85, v222
	ds_write_b128 v220, v[82:85]
	ds_write_b128 v220, v[86:89] offset:32
	ds_write_b128 v220, v[90:93] offset:64
	ds_write_b128 v220, v[94:97] offset:96
	ds_write_b128 v220, v[66:69] offset:128
	ds_write_b128 v220, v[70:73] offset:160
	ds_write_b128 v220, v[74:77] offset:192
	ds_write_b128 v220, v[78:81] offset:224
	v_mov_b32_e32 v230, v222
	v_add_u32_e32 v231, 0x2000, v222
	v_add_u32_e32 v232, 0x4000, v222
	v_add_u32_e32 v233, 0x6000, v222
	v_add_u32_e32 v234, 0x8000, v222
	v_add_u32_e32 v235, 0xa000, v222
	v_add_u32_e32 v236, 0xc000, v222
	v_add_u32_e32 v237, 0xe000, v222
	s_waitcnt lgkmcnt(0)
	ds_read_b128 v[82:85], v221
	ds_read_b128 v[86:89], v221 offset:1088
	ds_read_b128 v[90:93], v221 offset:2176
	ds_read_b128 v[94:97], v221 offset:3264
	ds_read_b128 v[66:69], v221 offset:4352
	ds_read_b128 v[70:73], v221 offset:5440
	ds_read_b128 v[74:77], v221 offset:6528
	ds_read_b128 v[78:81], v221 offset:7616
	s_waitcnt lgkmcnt(7)
	v_cvt_pk_bf16_f32 v82, v82, v83
	v_cvt_pk_bf16_f32 v83, v84, v85
	global_store_dwordx2 v230, v[82:83], s[82:83] sc1
	s_waitcnt lgkmcnt(6)
	v_cvt_pk_bf16_f32 v86, v86, v87
	v_cvt_pk_bf16_f32 v87, v88, v89
	global_store_dwordx2 v231, v[86:87], s[82:83] sc1
	s_waitcnt lgkmcnt(5)
	v_cvt_pk_bf16_f32 v90, v90, v91
	v_cvt_pk_bf16_f32 v91, v92, v93
	global_store_dwordx2 v232, v[90:91], s[82:83] sc1
	s_waitcnt lgkmcnt(4)
	v_cvt_pk_bf16_f32 v94, v94, v95
	v_cvt_pk_bf16_f32 v95, v96, v97
	global_store_dwordx2 v233, v[94:95], s[82:83] sc1
	s_waitcnt lgkmcnt(3)
	v_cvt_pk_bf16_f32 v66, v66, v67
	v_cvt_pk_bf16_f32 v67, v68, v69
	global_store_dwordx2 v234, v[66:67], s[82:83] sc1
	s_waitcnt lgkmcnt(2)
	v_cvt_pk_bf16_f32 v70, v70, v71
	v_cvt_pk_bf16_f32 v71, v72, v73
	global_store_dwordx2 v235, v[70:71], s[82:83] sc1
	s_waitcnt lgkmcnt(1)
	v_cvt_pk_bf16_f32 v74, v74, v75
	v_cvt_pk_bf16_f32 v75, v76, v77
	global_store_dwordx2 v236, v[74:75], s[82:83] sc1
	s_waitcnt lgkmcnt(0)
	v_cvt_pk_bf16_f32 v78, v78, v79
	v_cvt_pk_bf16_f32 v79, v80, v81
	global_store_dwordx2 v237, v[78:79], s[82:83] sc1
	ds_write_b128 v220, v[50:53]
	ds_write_b128 v220, v[54:57] offset:32
	ds_write_b128 v220, v[58:61] offset:64
	ds_write_b128 v220, v[62:65] offset:96
	ds_write_b128 v220, v[34:37] offset:128
	ds_write_b128 v220, v[38:41] offset:160
	ds_write_b128 v220, v[42:45] offset:192
	ds_write_b128 v220, v[46:49] offset:224
	v_add_u32_e32 v230, 0x10000, v222
	v_add_u32_e32 v231, 0x12000, v222
	v_add_u32_e32 v232, 0x14000, v222
	v_add_u32_e32 v233, 0x16000, v222
	v_add_u32_e32 v234, 0x18000, v222
	v_add_u32_e32 v235, 0x1a000, v222
	v_add_u32_e32 v236, 0x1c000, v222
	v_add_u32_e32 v237, 0x1e000, v222
	s_waitcnt lgkmcnt(0)
	ds_read_b128 v[50:53], v221
	ds_read_b128 v[54:57], v221 offset:1088
	ds_read_b128 v[58:61], v221 offset:2176
	ds_read_b128 v[62:65], v221 offset:3264
	ds_read_b128 v[34:37], v221 offset:4352
	ds_read_b128 v[38:41], v221 offset:5440
	ds_read_b128 v[42:45], v221 offset:6528
	ds_read_b128 v[46:49], v221 offset:7616
	s_waitcnt lgkmcnt(7)
	v_cvt_pk_bf16_f32 v50, v50, v51
	v_cvt_pk_bf16_f32 v51, v52, v53
	global_store_dwordx2 v230, v[50:51], s[82:83] sc1
	s_waitcnt lgkmcnt(6)
	v_cvt_pk_bf16_f32 v54, v54, v55
	v_cvt_pk_bf16_f32 v55, v56, v57
	global_store_dwordx2 v231, v[54:55], s[82:83] sc1
	s_waitcnt lgkmcnt(5)
	v_cvt_pk_bf16_f32 v58, v58, v59
	v_cvt_pk_bf16_f32 v59, v60, v61
	global_store_dwordx2 v232, v[58:59], s[82:83] sc1
	s_waitcnt lgkmcnt(4)
	v_cvt_pk_bf16_f32 v62, v62, v63
	v_cvt_pk_bf16_f32 v63, v64, v65
	global_store_dwordx2 v233, v[62:63], s[82:83] sc1
	s_waitcnt lgkmcnt(3)
	v_cvt_pk_bf16_f32 v34, v34, v35
	v_cvt_pk_bf16_f32 v35, v36, v37
	global_store_dwordx2 v234, v[34:35], s[82:83] sc1
	s_waitcnt lgkmcnt(2)
	v_cvt_pk_bf16_f32 v38, v38, v39
	v_cvt_pk_bf16_f32 v39, v40, v41
	global_store_dwordx2 v235, v[38:39], s[82:83] sc1
	s_waitcnt lgkmcnt(1)
	v_cvt_pk_bf16_f32 v42, v42, v43
	v_cvt_pk_bf16_f32 v43, v44, v45
	global_store_dwordx2 v236, v[42:43], s[82:83] sc1
	s_waitcnt lgkmcnt(0)
	v_cvt_pk_bf16_f32 v46, v46, v47
	v_cvt_pk_bf16_f32 v47, v48, v49
	global_store_dwordx2 v237, v[46:47], s[82:83] sc1
	ds_write_b128 v220, v[18:21]
	ds_write_b128 v220, v[22:25] offset:32
	ds_write_b128 v220, v[26:29] offset:64
	ds_write_b128 v220, v[30:33] offset:96
	ds_write_b128 v220, v[2:5] offset:128
	ds_write_b128 v220, v[6:9] offset:160
	ds_write_b128 v220, v[10:13] offset:192
	ds_write_b128 v220, v[14:17] offset:224
	v_add_u32_e32 v230, 0x20000, v222
	v_add_u32_e32 v231, 0x22000, v222
	v_add_u32_e32 v232, 0x24000, v222
	v_add_u32_e32 v233, 0x26000, v222
	v_add_u32_e32 v234, 0x28000, v222
	v_add_u32_e32 v235, 0x2a000, v222
	v_add_u32_e32 v236, 0x2c000, v222
	v_add_u32_e32 v237, 0x2e000, v222
	s_waitcnt lgkmcnt(0)
	ds_read_b128 v[18:21], v221
	ds_read_b128 v[22:25], v221 offset:1088
	ds_read_b128 v[26:29], v221 offset:2176
	ds_read_b128 v[30:33], v221 offset:3264
	ds_read_b128 v[2:5], v221 offset:4352
	ds_read_b128 v[6:9], v221 offset:5440
	ds_read_b128 v[10:13], v221 offset:6528
	ds_read_b128 v[14:17], v221 offset:7616
	s_waitcnt lgkmcnt(7)
	v_cvt_pk_bf16_f32 v18, v18, v19
	v_cvt_pk_bf16_f32 v19, v20, v21
	global_store_dwordx2 v230, v[18:19], s[82:83] sc1
	s_waitcnt lgkmcnt(6)
	v_cvt_pk_bf16_f32 v22, v22, v23
	v_cvt_pk_bf16_f32 v23, v24, v25
	global_store_dwordx2 v231, v[22:23], s[82:83] sc1
	s_waitcnt lgkmcnt(5)
	v_cvt_pk_bf16_f32 v26, v26, v27
	v_cvt_pk_bf16_f32 v27, v28, v29
	global_store_dwordx2 v232, v[26:27], s[82:83] sc1
	s_waitcnt lgkmcnt(4)
	v_cvt_pk_bf16_f32 v30, v30, v31
	v_cvt_pk_bf16_f32 v31, v32, v33
	global_store_dwordx2 v233, v[30:31], s[82:83] sc1
	s_waitcnt lgkmcnt(3)
	v_cvt_pk_bf16_f32 v2, v2, v3
	v_cvt_pk_bf16_f32 v3, v4, v5
	global_store_dwordx2 v234, v[2:3], s[82:83] sc1
	s_waitcnt lgkmcnt(2)
	v_cvt_pk_bf16_f32 v6, v6, v7
	v_cvt_pk_bf16_f32 v7, v8, v9
	global_store_dwordx2 v235, v[6:7], s[82:83] sc1
	s_waitcnt lgkmcnt(1)
	v_cvt_pk_bf16_f32 v10, v10, v11
	v_cvt_pk_bf16_f32 v11, v12, v13
	global_store_dwordx2 v236, v[10:11], s[82:83] sc1
	s_waitcnt lgkmcnt(0)
	v_cvt_pk_bf16_f32 v14, v14, v15
	v_cvt_pk_bf16_f32 v15, v16, v17
	global_store_dwordx2 v237, v[14:15], s[82:83] sc1
	s_barrier
	s_mov_b64 s[4:5], exec
	s_branch .LBB0_149
.LBB0_248:
	s_load_dword s66, s[0:1], 0x468
	s_waitcnt lgkmcnt(0)
	s_cmpk_lg_u32 s66, 0x200
	s_cbranch_scc1 FUSE2_ORIG
	s_cmp_lt_i32 s23, 4
	s_cbranch_scc1 FUSE2_ORIG
	s_waitcnt vmcnt(0)
	s_barrier
	v_bfe_u32 v5, v0, 6, 2
	s_and_b32 s73, s2, 0x1ff
	s_nop 1
	v_readfirstlane_b32 s67, v5
	s_cmp_lg_u32 s67, 0
	s_cbranch_scc1 FUSE2_WAIT
	s_and_b32 s67, s73, 63
	s_lshl_b32 s68, s67, 6
	s_and_b32 s69, s67, 32
	s_lshl_b32 s69, s69, 6
	s_add_u32 s68, s68, s69
	s_add_u32 s68, s68, 0x1c00
	v_mov_b32_e32 v2, s68
	s_sub_u32 s78, s67, 1
	s_max_i32 s78, s78, 0
	s_add_u32 s79, s67, 1
	s_min_i32 s79, s79, 63
	s_and_b32 s69, s78, 32
	s_lshl_b32 s69, s69, 6
	s_lshl_b32 s78, s78, 6
	s_add_u32 s78, s78, s69
	s_add_u32 s78, s78, 0x1c00
	s_and_b32 s69, s79, 32
	s_lshl_b32 s69, s69, 6
	s_lshl_b32 s79, s79, 6
	s_add_u32 s79, s79, s69
	s_add_u32 s79, s79, 0x1c00
	v_mov_b32_e32 v6, s78
	v_mov_b32_e32 v7, s79
	v_mov_b32_e32 v3, 1
	s_mov_b64 s[70:71], exec
	s_mov_b64 exec, 1
	s_mov_b32 s74, 0
	global_atomic_add v2, v3, s[20:21]
FUSE2_SPIN:
	global_load_dword v4, v2, s[20:21] sc1
	global_load_dword v8, v6, s[20:21] sc1
	global_load_dword v9, v7, s[20:21] sc1
	s_waitcnt vmcnt(0)
	v_min_u32_e32 v4, v4, v8
	v_min_u32_e32 v4, v4, v9
	s_nop 1
	v_readfirstlane_b32 s69, v4
	s_cmp_ge_u32 s69, 8
	s_cbranch_scc1 FUSE2_GOT
	s_add_i32 s74, s74, 1
	s_cmp_gt_u32 s74, 0x100000
	s_cbranch_scc1 FUSE2_GOT
	s_sleep 1
	s_branch FUSE2_SPIN
FUSE2_GOT:
	s_mov_b64 exec, s[70:71]
FUSE2_WAIT:
	s_barrier
	s_branch .LBB0_301
FUSE2_ORIG:
	s_cmp_lt_i32 s23, 4
	s_cbranch_scc1 .LBB0_301
	s_waitcnt vmcnt(0)
	v_and_b32_e32 v1, 0x3ff, v0
	v_cmp_eq_u32_e32 vcc, 0, v1
	v_mov_b32_e32 v2, v146
	v_mov_b32_e32 v4, v148
	s_waitcnt vmcnt(0) lgkmcnt(0)
	s_barrier
	s_and_saveexec_b64 s[4:5], vcc
	s_cbranch_execz .LBB0_298
	v_cmp_eq_u32_e32 vcc, 0, v148
	v_mov_b32_e32 v2, v146
	v_mov_b32_e32 v4, v148
	s_waitcnt vmcnt(0) expcnt(0) lgkmcnt(0)
	s_and_saveexec_b64 s[6:7], vcc
	s_cbranch_execz .LBB0_265
	s_load_dwordx2 s[12:13], s[0:1], 0x468
	s_load_dword s3, s[0:1], 0x470
	s_add_u32 s8, s20, 0x1000
	s_addc_u32 s9, s21, 0
	s_add_u32 s10, s20, 0x1100
	s_waitcnt lgkmcnt(0)
	s_mul_i32 s11, s13, s12
	s_mul_i32 s3, s11, s3
	s_addc_u32 s11, s21, 0
	s_add_u32 s12, s20, 0x1200
	s_addc_u32 s13, s21, 0
	s_add_u32 s14, s20, 0x1300
	s_addc_u32 s15, s21, 0
	s_mov_b32 s26, 1
	v_mov_b32_e32 v18, 0
	s_branch .LBB0_253

FUSE3_SPIN:
	global_load_dword v4, v2, s[20:21] sc1
	s_waitcnt vmcnt(0)
	v_readfirstlane_b32 s69, v4
	s_cmp_ge_u32 s69, 16
	s_cbranch_scc1 FUSE3_GOT
	s_add_i32 s74, s74, 1
	s_cmp_gt_u32 s74, 0x100000
	s_cbranch_scc1 FUSE3_GOT
	s_sleep 1
	s_branch FUSE3_SPIN

FUSE5_SPIN:
	global_load_dword v4, v2, s[20:21] sc1
	s_waitcnt vmcnt(0)
	v_readfirstlane_b32 s69, v4
	s_cmp_ge_u32 s69, 24
	s_cbranch_scc1 FUSE5_GOT
	s_add_i32 s74, s74, 1
	s_cmp_gt_u32 s74, 0x100000
	s_cbranch_scc1 FUSE5_GOT
	s_sleep 1
	s_branch FUSE5_SPIN

FUSE11_SPIN:
	global_load_dword v4, v2, s[20:21] sc1
	s_waitcnt vmcnt(0)
	v_readfirstlane_b32 s69, v4
	s_cmp_ge_u32 s69, 32
	s_cbranch_scc1 FUSE11_GOT
	s_add_i32 s74, s74, 1
	s_cmp_gt_u32 s74, 0x100000
	s_cbranch_scc1 FUSE11_GOT
	s_sleep 1
	s_branch FUSE11_SPIN

FUSE15_SPIN:
	global_load_dword v4, v2, s[20:21] sc1
	s_waitcnt vmcnt(0)
	v_readfirstlane_b32 s69, v4
	s_cmp_ge_u32 s69, 40
	s_cbranch_scc1 FUSE15_GOT
	s_add_i32 s74, s74, 1
	s_cmp_gt_u32 s74, 0x100000
	s_cbranch_scc1 FUSE15_GOT
	s_sleep 1
	s_branch FUSE15_SPIN

FUSE16_SPIN:
	global_load_dword v4, v2, s[20:21] sc1
	s_waitcnt vmcnt(0)
	v_readfirstlane_b32 s69, v4
	s_cmp_ge_u32 s69, 48
	s_cbranch_scc1 FUSE16_GOT
	s_add_i32 s74, s74, 1
	s_cmp_gt_u32 s74, 0x100000
	s_cbranch_scc1 FUSE16_GOT
	s_sleep 1
	s_branch FUSE16_SPIN

G1E_ph17_ST:
	v_and_b32_e32 v223, 31, v0
	v_mul_u32_u24_e32 v220, 0x110, v223
	v_bfe_u32 v223, v0, 5, 1
	v_lshl_add_u32 v220, v223, 4, v220
	v_bfe_u32 v224, v0, 6, 2
	v_mul_u32_u24_e32 v223, 0x2200, v224
	v_add_u32_e32 v220, v220, v223
	v_bfe_u32 v222, v0, 4, 2
	v_mul_u32_u24_e32 v221, 0x110, v222
	v_add_u32_e32 v221, v221, v223
	v_and_b32_e32 v223, 15, v0
	v_lshl_add_u32 v221, v223, 4, v221
	s_and_b32 s84, s35, 63
	s_mulk_i32 s84, 0xc0
	s_lshr_b32 s85, s35, 6
	s_and_b32 s85, s85, 7
	s_lshl_b32 s85, s85, 8
	v_lshrrev_b32_e32 v224, 1, v224
	v_mul_u32_u24_e32 v224, 0x60, v224
	v_add3_u32 v222, v222, v224, s84
	v_lshlrev_b32_e32 v222, 11, v222
	v_lshl_add_u32 v222, v223, 3, v222
	v_bfe_u32 v223, v0, 6, 1
	v_lshl_add_u32 v222, v223, 7, v222
	v_add_u32_e32 v222, s85, v222
	ds_write_b128 v220, v[82:85]
	ds_write_b128 v220, v[86:89] offset:32
	ds_write_b128 v220, v[90:93] offset:64
	ds_write_b128 v220, v[94:97] offset:96
	ds_write_b128 v220, v[66:69] offset:128
	ds_write_b128 v220, v[70:73] offset:160
	ds_write_b128 v220, v[74:77] offset:192
	ds_write_b128 v220, v[78:81] offset:224
	v_mov_b32_e32 v230, v222
	v_add_u32_e32 v231, 0x2000, v222
	v_add_u32_e32 v232, 0x4000, v222
	v_add_u32_e32 v233, 0x6000, v222
	v_add_u32_e32 v234, 0x8000, v222
	v_add_u32_e32 v235, 0xa000, v222
	v_add_u32_e32 v236, 0xc000, v222
	v_add_u32_e32 v237, 0xe000, v222
	s_waitcnt lgkmcnt(0)
	ds_read_b128 v[82:85], v221
	ds_read_b128 v[86:89], v221 offset:1088
	ds_read_b128 v[90:93], v221 offset:2176
	ds_read_b128 v[94:97], v221 offset:3264
	ds_read_b128 v[66:69], v221 offset:4352
	ds_read_b128 v[70:73], v221 offset:5440
	ds_read_b128 v[74:77], v221 offset:6528
	ds_read_b128 v[78:81], v221 offset:7616
	s_waitcnt lgkmcnt(7)
	v_cvt_pk_bf16_f32 v82, v82, v83
	v_cvt_pk_bf16_f32 v83, v84, v85
	global_store_dwordx2 v230, v[82:83], s[82:83] sc1
	s_waitcnt lgkmcnt(6)
	v_cvt_pk_bf16_f32 v86, v86, v87
	v_cvt_pk_bf16_f32 v87, v88, v89
	global_store_dwordx2 v231, v[86:87], s[82:83] sc1
	s_waitcnt lgkmcnt(5)
	v_cvt_pk_bf16_f32 v90, v90, v91
	v_cvt_pk_bf16_f32 v91, v92, v93
	global_store_dwordx2 v232, v[90:91], s[82:83] sc1
	s_waitcnt lgkmcnt(4)
	v_cvt_pk_bf16_f32 v94, v94, v95
	v_cvt_pk_bf16_f32 v95, v96, v97
	global_store_dwordx2 v233, v[94:95], s[82:83] sc1
	s_waitcnt lgkmcnt(3)
	v_cvt_pk_bf16_f32 v66, v66, v67
	v_cvt_pk_bf16_f32 v67, v68, v69
	global_store_dwordx2 v234, v[66:67], s[82:83] sc1
	s_waitcnt lgkmcnt(2)
	v_cvt_pk_bf16_f32 v70, v70, v71
	v_cvt_pk_bf16_f32 v71, v72, v73
	global_store_dwordx2 v235, v[70:71], s[82:83] sc1
	s_waitcnt lgkmcnt(1)
	v_cvt_pk_bf16_f32 v74, v74, v75
	v_cvt_pk_bf16_f32 v75, v76, v77
	global_store_dwordx2 v236, v[74:75], s[82:83] sc1
	s_waitcnt lgkmcnt(0)
	v_cvt_pk_bf16_f32 v78, v78, v79
	v_cvt_pk_bf16_f32 v79, v80, v81
	global_store_dwordx2 v237, v[78:79], s[82:83] sc1
	ds_write_b128 v220, v[50:53]
	ds_write_b128 v220, v[54:57] offset:32
	ds_write_b128 v220, v[58:61] offset:64
	ds_write_b128 v220, v[62:65] offset:96
	ds_write_b128 v220, v[34:37] offset:128
	ds_write_b128 v220, v[38:41] offset:160
	ds_write_b128 v220, v[42:45] offset:192
	ds_write_b128 v220, v[46:49] offset:224
	v_add_u32_e32 v230, 0x10000, v222
	v_add_u32_e32 v231, 0x12000, v222
	v_add_u32_e32 v232, 0x14000, v222
	v_add_u32_e32 v233, 0x16000, v222
	v_add_u32_e32 v234, 0x18000, v222
	v_add_u32_e32 v235, 0x1a000, v222
	v_add_u32_e32 v236, 0x1c000, v222
	v_add_u32_e32 v237, 0x1e000, v222
	s_waitcnt lgkmcnt(0)
	ds_read_b128 v[50:53], v221
	ds_read_b128 v[54:57], v221 offset:1088
	ds_read_b128 v[58:61], v221 offset:2176
	ds_read_b128 v[62:65], v221 offset:3264
	ds_read_b128 v[34:37], v221 offset:4352
	ds_read_b128 v[38:41], v221 offset:5440
	ds_read_b128 v[42:45], v221 offset:6528
	ds_read_b128 v[46:49], v221 offset:7616
	s_waitcnt lgkmcnt(7)
	v_cvt_pk_bf16_f32 v50, v50, v51
	v_cvt_pk_bf16_f32 v51, v52, v53
	global_store_dwordx2 v230, v[50:51], s[82:83] sc1
	s_waitcnt lgkmcnt(6)
	v_cvt_pk_bf16_f32 v54, v54, v55
	v_cvt_pk_bf16_f32 v55, v56, v57
	global_store_dwordx2 v231, v[54:55], s[82:83] sc1
	s_waitcnt lgkmcnt(5)
	v_cvt_pk_bf16_f32 v58, v58, v59
	v_cvt_pk_bf16_f32 v59, v60, v61
	global_store_dwordx2 v232, v[58:59], s[82:83] sc1
	s_waitcnt lgkmcnt(4)
	v_cvt_pk_bf16_f32 v62, v62, v63
	v_cvt_pk_bf16_f32 v63, v64, v65
	global_store_dwordx2 v233, v[62:63], s[82:83] sc1
	s_waitcnt lgkmcnt(3)
	v_cvt_pk_bf16_f32 v34, v34, v35
	v_cvt_pk_bf16_f32 v35, v36, v37
	global_store_dwordx2 v234, v[34:35], s[82:83] sc1
	s_waitcnt lgkmcnt(2)
	v_cvt_pk_bf16_f32 v38, v38, v39
	v_cvt_pk_bf16_f32 v39, v40, v41
	global_store_dwordx2 v235, v[38:39], s[82:83] sc1
	s_waitcnt lgkmcnt(1)
	v_cvt_pk_bf16_f32 v42, v42, v43
	v_cvt_pk_bf16_f32 v43, v44, v45
	global_store_dwordx2 v236, v[42:43], s[82:83] sc1
	s_waitcnt lgkmcnt(0)
	v_cvt_pk_bf16_f32 v46, v46, v47
	v_cvt_pk_bf16_f32 v47, v48, v49
	global_store_dwordx2 v237, v[46:47], s[82:83] sc1
	ds_write_b128 v220, v[18:21]
	ds_write_b128 v220, v[22:25] offset:32
	ds_write_b128 v220, v[26:29] offset:64
	ds_write_b128 v220, v[30:33] offset:96
	ds_write_b128 v220, v[2:5] offset:128
	ds_write_b128 v220, v[6:9] offset:160
	ds_write_b128 v220, v[10:13] offset:192
	ds_write_b128 v220, v[14:17] offset:224
	v_add_u32_e32 v230, 0x20000, v222
	v_add_u32_e32 v231, 0x22000, v222
	v_add_u32_e32 v232, 0x24000, v222
	v_add_u32_e32 v233, 0x26000, v222
	v_add_u32_e32 v234, 0x28000, v222
	v_add_u32_e32 v235, 0x2a000, v222
	v_add_u32_e32 v236, 0x2c000, v222
	v_add_u32_e32 v237, 0x2e000, v222
	s_waitcnt lgkmcnt(0)
	ds_read_b128 v[18:21], v221
	ds_read_b128 v[22:25], v221 offset:1088
	ds_read_b128 v[26:29], v221 offset:2176
	ds_read_b128 v[30:33], v221 offset:3264
	ds_read_b128 v[2:5], v221 offset:4352
	ds_read_b128 v[6:9], v221 offset:5440
	ds_read_b128 v[10:13], v221 offset:6528
	ds_read_b128 v[14:17], v221 offset:7616
	s_waitcnt lgkmcnt(7)
	v_cvt_pk_bf16_f32 v18, v18, v19
	v_cvt_pk_bf16_f32 v19, v20, v21
	global_store_dwordx2 v230, v[18:19], s[82:83] sc1
	s_waitcnt lgkmcnt(6)
	v_cvt_pk_bf16_f32 v22, v22, v23
	v_cvt_pk_bf16_f32 v23, v24, v25
	global_store_dwordx2 v231, v[22:23], s[82:83] sc1
	s_waitcnt lgkmcnt(5)
	v_cvt_pk_bf16_f32 v26, v26, v27
	v_cvt_pk_bf16_f32 v27, v28, v29
	global_store_dwordx2 v232, v[26:27], s[82:83] sc1
	s_waitcnt lgkmcnt(4)
	v_cvt_pk_bf16_f32 v30, v30, v31
	v_cvt_pk_bf16_f32 v31, v32, v33
	global_store_dwordx2 v233, v[30:31], s[82:83] sc1
	s_waitcnt lgkmcnt(3)
	v_cvt_pk_bf16_f32 v2, v2, v3
	v_cvt_pk_bf16_f32 v3, v4, v5
	global_store_dwordx2 v234, v[2:3], s[82:83] sc1
	s_waitcnt lgkmcnt(2)
	v_cvt_pk_bf16_f32 v6, v6, v7
	v_cvt_pk_bf16_f32 v7, v8, v9
	global_store_dwordx2 v235, v[6:7], s[82:83] sc1
	s_waitcnt lgkmcnt(1)
	v_cvt_pk_bf16_f32 v10, v10, v11
	v_cvt_pk_bf16_f32 v11, v12, v13
	global_store_dwordx2 v236, v[10:11], s[82:83] sc1
	s_waitcnt lgkmcnt(0)
	v_cvt_pk_bf16_f32 v14, v14, v15
	v_cvt_pk_bf16_f32 v15, v16, v17
	global_store_dwordx2 v237, v[14:15], s[82:83] sc1
	s_barrier
	s_mov_b64 s[4:5], exec
	s_branch .LBB0_1991
.LBB0_2090:
	s_load_dword s66, s[0:1], 0x468
	s_waitcnt lgkmcnt(0)
	s_cmpk_lg_u32 s66, 0x200
	s_cbranch_scc1 FUSE17_ORIG
	s_cmp_lt_i32 s23, 19
	s_cbranch_scc1 FUSE17_ORIG
	s_waitcnt vmcnt(0)
	s_barrier
	v_bfe_u32 v5, v0, 6, 2
	s_and_b32 s73, s2, 0x1ff
	s_nop 1
	v_readfirstlane_b32 s67, v5
	s_cmp_lg_u32 s67, 0
	s_cbranch_scc1 FUSE17_WAIT
	s_and_b32 s67, s73, 63
	s_lshl_b32 s68, s67, 6
	s_and_b32 s69, s67, 32
	s_lshl_b32 s69, s69, 6
	s_add_u32 s68, s68, s69
	s_add_u32 s68, s68, 0x1c00
	v_mov_b32_e32 v2, s68
	s_sub_u32 s78, s67, 1
	s_max_i32 s78, s78, 0
	s_add_u32 s79, s67, 1
	s_min_i32 s79, s79, 63
	s_and_b32 s69, s78, 32
	s_lshl_b32 s69, s69, 6
	s_lshl_b32 s78, s78, 6
	s_add_u32 s78, s78, s69
	s_add_u32 s78, s78, 0x1c00
	s_and_b32 s69, s79, 32
	s_lshl_b32 s69, s69, 6
	s_lshl_b32 s79, s79, 6
	s_add_u32 s79, s79, s69
	s_add_u32 s79, s79, 0x1c00
	v_mov_b32_e32 v6, s78
	v_mov_b32_e32 v7, s79
	v_mov_b32_e32 v3, 1
	s_mov_b64 s[70:71], exec
	s_mov_b64 exec, 1
	s_mov_b32 s74, 0
	global_atomic_add v2, v3, s[20:21]
FUSE17_SPIN:
	global_load_dword v4, v2, s[20:21] sc1
	global_load_dword v8, v6, s[20:21] sc1
	global_load_dword v9, v7, s[20:21] sc1
	s_waitcnt vmcnt(0)
	v_min_u32_e32 v4, v4, v8
	v_min_u32_e32 v4, v4, v9
	s_nop 1
	v_readfirstlane_b32 s69, v4
	s_cmp_ge_u32 s69, 56
	s_cbranch_scc1 FUSE17_GOT
	s_add_i32 s74, s74, 1
	s_cmp_gt_u32 s74, 0x100000
	s_cbranch_scc1 FUSE17_GOT
	s_sleep 1
	s_branch FUSE17_SPIN
FUSE17_GOT:
	s_mov_b64 exec, s[70:71]
	buffer_inv sc1
	s_waitcnt vmcnt(0)
FUSE17_WAIT:
	s_barrier
	s_branch .LBB0_2143
FUSE17_ORIG:
	s_cmp_lt_i32 s23, 19
	s_cbranch_scc1 .LBB0_2143
	s_waitcnt vmcnt(0)
	s_waitcnt vmcnt(0)
	v_and_b32_e32 v3, 0x3ff, v0
	v_cmp_eq_u32_e32 vcc, 0, v3
	v_mov_b32_e32 v2, v146
	v_mov_b32_e32 v4, v148
	s_barrier
	s_and_saveexec_b64 s[4:5], vcc
	s_cbranch_execz .LBB0_2140
	v_cmp_eq_u32_e32 vcc, 0, v148
	v_mov_b32_e32 v2, v146
	v_mov_b32_e32 v4, v148
	s_waitcnt vmcnt(0) expcnt(0) lgkmcnt(0)
	s_and_saveexec_b64 s[6:7], vcc
	s_cbranch_execz .LBB0_2107
	s_load_dwordx2 s[12:13], s[0:1], 0x468
	s_load_dword s3, s[0:1], 0x470
	s_add_u32 s8, s20, 0x1000
	s_addc_u32 s9, s21, 0
	s_add_u32 s10, s20, 0x1100
	s_waitcnt lgkmcnt(0)
	s_mul_i32 s11, s13, s12
	s_mul_i32 s3, s11, s3
	s_addc_u32 s11, s21, 0
	s_add_u32 s12, s20, 0x1200
	s_addc_u32 s13, s21, 0
	s_add_u32 s14, s20, 0x1300
	s_addc_u32 s15, s21, 0
	s_mov_b32 s26, 1
	v_mov_b32_e32 v19, 0
	s_branch .LBB0_2095

FUSE18_SPIN:
	global_load_dword v4, v2, s[20:21] sc1
	s_waitcnt vmcnt(0)
	v_readfirstlane_b32 s69, v4
	s_cmp_ge_u32 s69, 64
	s_cbranch_scc1 FUSE18_GOT
	s_add_i32 s74, s74, 1
	s_cmp_gt_u32 s74, 0x100000
	s_cbranch_scc1 FUSE18_GOT
	s_sleep 1
	s_branch FUSE18_SPIN

FUSE20_SPIN:
	global_load_dword v4, v2, s[20:21] sc1
	s_waitcnt vmcnt(0)
	v_readfirstlane_b32 s69, v4
	s_cmp_ge_u32 s69, 72
	s_cbranch_scc1 FUSE20_GOT
	s_add_i32 s74, s74, 1
	s_cmp_gt_u32 s74, 0x100000
	s_cbranch_scc1 FUSE20_GOT
	s_sleep 1
	s_branch FUSE20_SPIN
